# P0 w_in transpose loop software-pipelined by one tile (next tile's data and row-scale loads in flight during the LDS half), second row-scale load no longer serialized
# baseline (speedup 1.0000x reference)
; __device__ void transpose_bf16(const float* __restrict__ src, int Kr, int Nc, u16* __restrict__ dst, const float* __restrict__ rowscale, char* lds, int bid, int nb) {
;     ...
;   for (int t = bid; t < tk * tn; t += nb) {
;     const int k0 = (t / tn) * 64, c0 = (t % tn) * 64;
; #pragma unroll
;     for (int i = 0; i < 2; ++i) {
;       const int r = (tid >> 4) + 32 * i, c4 = (tid & 15) * 4;
;       f32x4 v = *(const f32x4*)(src + (size_t)(k0 + r) * Nc + c0 + c4);
;       const float sc = rowscale ? rowscale[k0 + r] : 1.f;
; #pragma unroll
;       for (int e = 0; e < 4; ++e) ts[(c4 + e) * 65 + r] = v[e] * sc;
;     }
;     __syncthreads();
.LBB0_19:
	s_mul_hi_i32 s12, s20, 0x3e0f83e1
	s_lshr_b32 s13, s12, 31
	s_ashr_i32 s12, s12, 4
	s_add_i32 s13, s12, s13
	s_lshl_b32 s12, s13, 6
	s_mulk_i32 s13, 0xef80
	s_add_i32 s14, s3, s13
	s_ashr_i32 s15, s14, 31
	v_lshl_add_u64 v[2:3], s[14:15], 2, v[12:13]
	v_or_b32_e32 v4, s12, v50
	v_mad_i64_i32 v[6:7], s[16:17], v4, s19, v[2:3]
	global_load_dwordx4 v[20:23], v[6:7], off
	v_add_u32_e32 v8, s12, v1
	v_mad_i64_i32 v[2:3], s[16:17], v8, s19, v[2:3]
	global_load_dwordx4 v[24:27], v[2:3], off
	s_and_b64 vcc, exec, s[4:5]
	s_cbranch_vccnz .Lp0_nosc_a
	v_ashrrev_i32_e32 v5, 31, v4
	v_lshl_add_u64 v[4:5], v[4:5], 2, s[8:9]
	global_load_dword v28, v[4:5], off
	s_ashr_i32 s13, s12, 31
	v_lshl_add_u64 v[6:7], s[12:13], 0, v[50:51]
	v_lshl_add_u64 v[6:7], v[6:7], 2, s[8:9]
	global_load_dword v29, v[6:7], off offset:128
	s_branch .Lp0_scdone_a
.Lp0_nosc_a:
	v_mov_b32_e32 v28, 1.0
	v_mov_b32_e32 v29, 1.0
.Lp0_scdone_a:
	s_mov_b32 s91, s14
	s_mov_b32 s92, s12
	s_ashr_i32 s93, s12, 31
	s_waitcnt vmcnt(0)
.Lp0_loop:
	s_waitcnt vmcnt(1)
	v_mul_f32_e32 v30, v20, v28
	v_mul_f32_e32 v31, v21, v28
	v_mul_f32_e32 v32, v22, v28
	v_mul_f32_e32 v33, v23, v28
	v_mul_f32_e32 v34, v24, v29
	v_mul_f32_e32 v35, v25, v29
	v_mul_f32_e32 v36, v26, v29
	v_mul_f32_e32 v37, v27, v29
	ds_write2_b32 v16, v30, v31 offset1:65
	ds_write2_b32 v16, v32, v33 offset0:130 offset1:195
	ds_write2_b32 v16, v34, v35 offset0:32 offset1:97
	ds_write2_b32 v16, v36, v37 offset0:162 offset1:227
	s_add_i32 s20, s20, s50
	s_add_i32 s3, s3, s18
	s_mov_b32 s90, 0
	s_cmpk_lt_i32 s20, 0x420
	s_cbranch_scc0 .Lp0_nonext
	s_mov_b32 s90, 1
	s_mul_hi_i32 s12, s20, 0x3e0f83e1
	s_lshr_b32 s13, s12, 31
	s_ashr_i32 s12, s12, 4
	s_add_i32 s13, s12, s13
	s_lshl_b32 s12, s13, 6
	s_mulk_i32 s13, 0xef80
	s_add_i32 s14, s3, s13
	s_ashr_i32 s15, s14, 31
	v_lshl_add_u64 v[2:3], s[14:15], 2, v[12:13]
	v_or_b32_e32 v4, s12, v50
	v_mad_i64_i32 v[6:7], s[16:17], v4, s19, v[2:3]
	global_load_dwordx4 v[20:23], v[6:7], off
	v_add_u32_e32 v8, s12, v1
	v_mad_i64_i32 v[2:3], s[16:17], v8, s19, v[2:3]
	global_load_dwordx4 v[24:27], v[2:3], off
	s_and_b64 vcc, exec, s[4:5]
	s_cbranch_vccnz .Lp0_nosc_b
	v_ashrrev_i32_e32 v5, 31, v4
	v_lshl_add_u64 v[4:5], v[4:5], 2, s[8:9]
	global_load_dword v28, v[4:5], off
	s_ashr_i32 s13, s12, 31
	v_lshl_add_u64 v[6:7], s[12:13], 0, v[50:51]
	v_lshl_add_u64 v[6:7], v[6:7], 2, s[8:9]
	global_load_dword v29, v[6:7], off offset:128
	s_branch .Lp0_scdone_b

; __device__ __forceinline__ unsigned pk2(float lo, float hi) { f32x2_t v = {lo, hi}; bf16x2_t b = __builtin_convertvector(v, bf16x2_t); return __builtin_bit_cast(unsigned, b); }
; __device__ void transpose_bf16(const float* __restrict__ src, int Kr, int Nc, u16* __restrict__ dst, const float* __restrict__ rowscale, char* lds, int bid, int nb) {
;     ...
;     __syncthreads();
;     {
;       const int c = tid >> 3, ch = tid & 7;
;       const float* tp = ts + c * 65 + ch * 8;
;       u32x4 w; w.x = pk2(tp[0], tp[1]); w.y = pk2(tp[2], tp[3]); w.z = pk2(tp[4], tp[5]); w.w = pk2(tp[6], tp[7]);
;       *(u32x4*)(dst + (size_t)(c0 + c) * Kr + k0 + ch * 8) = w;
;     }
;     __syncthreads();
;   }
.Lp0_scdone_b:
.Lp0_nonext:
	s_waitcnt lgkmcnt(0)
	s_barrier
	ds_read2_b32 v[2:3], v15 offset1:1
	ds_read2_b32 v[4:5], v15 offset0:2 offset1:3
	ds_read2_b32 v[6:7], v15 offset0:4 offset1:5
	ds_read2_b32 v[8:9], v15 offset0:6 offset1:7
	s_waitcnt lgkmcnt(3)
	v_cvt_pk_bf16_f32 v2, v2, v3
	s_waitcnt lgkmcnt(2)
	v_cvt_pk_bf16_f32 v3, v4, v5
	s_waitcnt lgkmcnt(1)
	v_cvt_pk_bf16_f32 v4, v6, v7
	v_add_u32_e32 v6, s91, v240
	v_ashrrev_i32_e32 v7, 31, v6
	v_lshlrev_b64 v[6:7], 11, v[6:7]
	v_lshl_add_u64 v[6:7], s[6:7], 0, v[6:7]
	v_lshl_add_u64 v[6:7], s[92:93], 1, v[6:7]
	s_waitcnt lgkmcnt(0)
	v_cvt_pk_bf16_f32 v5, v8, v9
	v_lshl_add_u64 v[6:7], v[6:7], 0, v[10:11]
	global_store_dwordx4 v[6:7], v[2:5], off
	s_barrier
	s_mov_b32 s91, s14
	s_mov_b32 s92, s12
	s_ashr_i32 s93, s12, 31
	s_cmp_eq_u32 s90, 1
	s_cbranch_scc1 .Lp0_loop
